# MLA QK^T K-fragment LDS prefetch 12 deep (on top of in-place O accumulators + pipelined partial sums)
# speedup vs baseline: 1.0166x; 1.0097x over previous
; #define LAS __attribute__((address_space(3)))
; template <int TYPE>
; __device__ __forceinline__ void attn_item(const Params& p, int layer, int head, int qb, int mode, LAS unsigned char* lds) {
;     ...
;         if (kbase <= w_last) {
;             f32x16 p0 = (f32x16){}, p1 = (f32x16){};
;             const LAS unsigned char* kt = K_lds + bf * SHM_K;
; #pragma unroll
;             for (int d0 = 0; d0 < NQ; ++d0) {
;                 const LAS unsigned char* a = d0 < 8 ? kt + kb[d0 & 3] + (d0 >> 2) * 128 : kt + kbr[d0 & 3];
;                 const bf16x8 b0 = *(const LAS bf16x8*)a, b1 = *(const LAS bf16x8*)(a + (d0 < 8 ? 32 * 256 : 32 * 128));
;                 p0 = __builtin_amdgcn_mfma_f32_32x32x16_bf16(b0, qr[d0], p0, 0, 0, 0);
;                 p1 = __builtin_amdgcn_mfma_f32_32x32x16_bf16(b1, qr[d0], p1, 0, 0, 0);
;                 if ((d0 & 3) == 3) SBAR();
;             }
;             if (TYPE == 1) {
;                 const LAS float* bb = B_lds + bf * 64 + 4 * hi;
; #pragma unroll
;                 for (int q4 = 0; q4 < 4; ++q4) {
;                     const f32x4 b0 = *(const LAS f32x4*)(bb + 8 * q4), b1 = *(const LAS f32x4*)(bb + 32 + 8 * q4);
; #pragma unroll
;                     for (int j = 0; j < 4; ++j) { p0[q4 * 4 + j] += b0[j]; p1[q4 * 4 + j] += b1[j]; }
;                 }
;             }
;             if (TYPE == 1 && kbase + 63 > w_first) {
;                 const int lim = my_kmax - kbase - 4 * hi; const float NEGI = -__builtin_inff();
; #pragma unroll
;                 for (int r = 0; r < 16; ++r) { const int c = (r & 3) + 8 * (r >> 2); if (c > lim) p0[r] = NEGI; if (c + 32 > lim) p1[r] = NEGI; }
;             }
;             if (t == T0) {
;                 const int lo = (PADR & 63) - 4 * hi; const float NEGI = -__builtin_inff();
; #pragma unroll
;                 for (int r = 0; r < 16; ++r) { const int c = (r & 3) + 8 * (r >> 2); if (c < lo) p0[r] = NEGI; if (c + 32 < lo) p1[r] = NEGI; }
;             }
;             float pmax = p0[0];
; #pragma unroll
;             for (int r = 1; r < 16; ++r) pmax = fmaxf(pmax, p0[r]);
; #pragma unroll
;             for (int r = 0; r < 16; ++r) pmax = fmaxf(pmax, p1[r]);
;             { auto rr = __builtin_amdgcn_permlane32_swap(__float_as_uint(pmax), __float_as_uint(pmax), false, false);
;               pmax = fmaxf(__uint_as_float(rr[0]), __uint_as_float(rr[1])); }
;             float mn, alpha;
.LBB0_821:
	s_cmp_gt_i32 s11, s10
	s_cbranch_scc1 .LBB0_818
	s_mul_i32 s19, s28, 0x6000
	s_add_i32 s19, s19, 0
	v_add_u32_e32 v102, s19, v230
	v_add_u32_e32 v103, v102, v228
	v_add_u32_e32 v104, s19, v231
	v_add_u32_e32 v105, v104, v228
	v_add_u32_e32 v106, s19, v232
	v_add_u32_e32 v107, v106, v228
	v_add_u32_e32 v108, s19, v233
	v_add_u32_e32 v109, v108, v228
	v_add_u32_e32 v248, v102, v229
	v_add_u32_e32 v249, v104, v229
	v_add_u32_e32 v250, v106, v229
	v_add_u32_e32 v251, v108, v229
	ds_read_b128 v[98:101], v103 offset:32768
	ds_read_b128 v[110:113], v103 offset:40960
	ds_read_b128 v[114:117], v105 offset:32768
	ds_read_b128 v[118:121], v105 offset:40960
	ds_read_b128 v[122:125], v107 offset:32768
	ds_read_b128 v[126:129], v107 offset:40960
	ds_read_b128 v[178:181], v109 offset:32768
	ds_read_b128 v[182:185], v109 offset:40960
	ds_read_b128 v[186:189], v103 offset:32896
	ds_read_b128 v[190:193], v103 offset:41088
	ds_read_b128 v[240:243], v105 offset:32896
	ds_read_b128 v[244:247], v105 offset:41088
	s_waitcnt lgkmcnt(11)
	v_mfma_f32_32x32x16_bf16 v[82:97], v[98:101], v[130:133], 0
	ds_read_b128 v[98:101], v107 offset:32896
	s_waitcnt lgkmcnt(11)
	v_mfma_f32_32x32x16_bf16 v[66:81], v[110:113], v[130:133], 0
	ds_read_b128 v[110:113], v107 offset:41088
	s_waitcnt lgkmcnt(11)
	v_mfma_f32_32x32x16_bf16 v[82:97], v[114:117], v[134:137], v[82:97]
	ds_read_b128 v[114:117], v109 offset:32896
	s_waitcnt lgkmcnt(11)
	v_mfma_f32_32x32x16_bf16 v[66:81], v[118:121], v[134:137], v[66:81]
	ds_read_b128 v[118:121], v109 offset:41088
	s_waitcnt lgkmcnt(11)
	v_mfma_f32_32x32x16_bf16 v[82:97], v[122:125], v[138:141], v[82:97]
	ds_read_b128 v[122:125], v248 offset:49152
	s_waitcnt lgkmcnt(11)
	v_mfma_f32_32x32x16_bf16 v[66:81], v[126:129], v[138:141], v[66:81]
	ds_read_b128 v[126:129], v248 offset:53248
	s_waitcnt lgkmcnt(11)
	v_mfma_f32_32x32x16_bf16 v[82:97], v[178:181], v[142:145], v[82:97]
	ds_read_b128 v[178:181], v249 offset:49152
	s_waitcnt lgkmcnt(11)
	v_mfma_f32_32x32x16_bf16 v[66:81], v[182:185], v[142:145], v[66:81]
	ds_read_b128 v[182:185], v249 offset:53248
	s_waitcnt lgkmcnt(11)
	v_mfma_f32_32x32x16_bf16 v[82:97], v[186:189], v[146:149], v[82:97]
	ds_read_b128 v[186:189], v250 offset:49152
	s_waitcnt lgkmcnt(11)
	v_mfma_f32_32x32x16_bf16 v[66:81], v[190:193], v[146:149], v[66:81]
	ds_read_b128 v[190:193], v250 offset:53248
	s_waitcnt lgkmcnt(11)
	v_mfma_f32_32x32x16_bf16 v[82:97], v[240:243], v[150:153], v[82:97]
	ds_read_b128 v[240:243], v251 offset:49152
	s_waitcnt lgkmcnt(11)
	v_mfma_f32_32x32x16_bf16 v[66:81], v[244:247], v[150:153], v[66:81]
	ds_read_b128 v[244:247], v251 offset:53248
	s_waitcnt lgkmcnt(11)
	v_mfma_f32_32x32x16_bf16 v[82:97], v[98:101], v[154:157], v[82:97]
	s_waitcnt lgkmcnt(10)
	v_mfma_f32_32x32x16_bf16 v[66:81], v[110:113], v[154:157], v[66:81]
	s_waitcnt lgkmcnt(9)
	v_mfma_f32_32x32x16_bf16 v[82:97], v[114:117], v[158:161], v[82:97]
	s_waitcnt lgkmcnt(8)
	v_mfma_f32_32x32x16_bf16 v[66:81], v[118:121], v[158:161], v[66:81]
	s_waitcnt lgkmcnt(7)
	v_mfma_f32_32x32x16_bf16 v[82:97], v[122:125], v[162:165], v[82:97]
	s_waitcnt lgkmcnt(6)
	v_mfma_f32_32x32x16_bf16 v[66:81], v[126:129], v[162:165], v[66:81]
	s_waitcnt lgkmcnt(5)
	v_mfma_f32_32x32x16_bf16 v[82:97], v[178:181], v[166:169], v[82:97]
	s_waitcnt lgkmcnt(4)
	v_mfma_f32_32x32x16_bf16 v[66:81], v[182:185], v[166:169], v[66:81]
	s_waitcnt lgkmcnt(3)
	v_mfma_f32_32x32x16_bf16 v[82:97], v[186:189], v[170:173], v[82:97]
	s_waitcnt lgkmcnt(2)
	v_mfma_f32_32x32x16_bf16 v[66:81], v[190:193], v[170:173], v[66:81]
	s_waitcnt lgkmcnt(1)
	v_mfma_f32_32x32x16_bf16 v[82:97], v[240:243], v[174:177], v[82:97]
	s_waitcnt lgkmcnt(0)
	v_mfma_f32_32x32x16_bf16 v[66:81], v[244:247], v[174:177], v[66:81]
	s_cmp_eq_u32 s18, 3
	s_cselect_b64 vcc, -1, 0
	s_nop 7
	v_cndmask_b32_e32 v82, v82, v219, vcc
	v_cndmask_b32_e32 v83, v83, v219, vcc
	v_max_f32_e32 v98, v83, v83
	v_max_f32_e32 v99, v82, v82
	v_cndmask_b32_e32 v85, v85, v219, vcc
	v_cndmask_b32_e32 v84, v84, v219, vcc
	v_max_f32_e32 v98, v99, v98
	v_cndmask_b32_e32 v87, v87, v219, vcc
	v_cndmask_b32_e32 v86, v86, v219, vcc
	v_max3_f32 v98, v98, v84, v85
	v_cndmask_b32_e32 v89, v89, v219, vcc
	v_cndmask_b32_e32 v88, v88, v219, vcc
	v_max3_f32 v98, v98, v86, v87
	v_cndmask_b32_e32 v91, v91, v219, vcc
	v_cndmask_b32_e32 v90, v90, v219, vcc
	v_max3_f32 v98, v98, v88, v89
	v_cndmask_b32_e32 v93, v93, v219, vcc
	v_cndmask_b32_e32 v92, v92, v219, vcc
	v_max3_f32 v98, v98, v90, v91
	v_cndmask_b32_e32 v95, v95, v219, vcc
	v_cndmask_b32_e32 v94, v94, v219, vcc
	v_max3_f32 v98, v98, v92, v93
	v_cndmask_b32_e32 v97, v97, v219, vcc
	v_cndmask_b32_e32 v96, v96, v219, vcc
	v_max3_f32 v98, v98, v94, v95
	v_cndmask_b32_e32 v67, v67, v219, vcc
	v_cndmask_b32_e32 v66, v66, v219, vcc
	v_max3_f32 v98, v98, v96, v97
	v_cndmask_b32_e32 v69, v69, v219, vcc
	v_cndmask_b32_e32 v68, v68, v219, vcc
	v_max3_f32 v98, v98, v66, v67
	v_cndmask_b32_e32 v71, v71, v219, vcc
	v_cndmask_b32_e32 v70, v70, v219, vcc
	v_max3_f32 v98, v98, v68, v69
	v_cndmask_b32_e32 v73, v73, v219, vcc
	v_cndmask_b32_e32 v72, v72, v219, vcc
	v_max3_f32 v98, v98, v70, v71
	v_max3_f32 v98, v98, v72, v73
	v_max3_f32 v98, v98, v74, v75
	v_max3_f32 v98, v98, v76, v77
	v_max3_f32 v98, v98, v78, v79
	v_max3_f32 v98, v98, v80, v81
	v_mov_b32_e32 v99, v98
	s_nop 1
	v_permlane32_swap_b32_e32 v98, v99
	v_max_f32_e32 v99, v99, v99
	v_max_f32_e32 v98, v98, v98
	v_max_f32_e32 v98, v98, v99
	v_sub_f32_e32 v99, v98, v198
	s_mov_b32 s18, 0x41380000
	v_cmp_ge_f32_e32 vcc, s18, v99
	s_cmp_eq_u64 vcc, exec
; __device__ __forceinline__ int crow(int r, int hi) { return (r & 3) + 8 * (r >> 2) + 4 * hi; }
; template <int TYPE>
; __device__ __forceinline__ void attn_item(const Params& p, int layer, int head, int qb, int mode, LAS unsigned char* lds) {
;     ...
;             float mn, alpha;
;             if (__all((pmax - m_reg) <= (TYPE == 1 ? 2.0f : 11.5f))) { mn = m_reg; alpha = 1.f; }
;             else { mn = fmaxf(m_reg, pmax); alpha = __builtin_amdgcn_exp2f(m_reg - mn); m_reg = mn; }
;             float ps = 0.f;
; #pragma unroll
;             for (int r = 0; r < 16; ++r) { p0[r] = __builtin_amdgcn_exp2f(p0[r] - mn); p1[r] = __builtin_amdgcn_exp2f(p1[r] - mn); ps += p0[r] + p1[r]; }
;             { auto rr = __builtin_amdgcn_permlane32_swap(__float_as_uint(ps), __float_as_uint(ps), false, false);
;               ps = __uint_as_float(rr[0]) + __uint_as_float(rr[1]); }
;             l_reg = l_reg * alpha + ps;
;             bf16x8 pa0, pa1, pa2, pa3;
;     ...
;             PK4(p0, 0, pa0); PK4(p0, 8, pa1); PK4(p1, 0, pa2); PK4(p1, 8, pa3);
;     ...
;             if (__any(alpha < 1.f)) {
;                 if (hi == 0) wsl[r32] = alpha;
;                 asm volatile("s_waitcnt lgkmcnt(0)" ::: "memory");
; #pragma unroll
;                 for (int r = 0; r < 16; ++r) { const float al = wsl[crow(r, hi)];
; #pragma unroll
;                     for (int d = 0; d < 4; ++d) o[d][r] *= al; }
;             }
	v_max_f32_e32 v99, v198, v198
	v_max_f32_e32 v98, v99, v98
	s_cselect_b64 vcc, -1, 0
	v_sub_f32_e32 v99, v198, v98
	v_cndmask_b32_e32 v198, v98, v198, vcc
	v_sub_f32_e32 v82, v82, v198
	v_sub_f32_e32 v66, v66, v198
	v_exp_f32_e32 v82, v82
	v_exp_f32_e32 v66, v66
	v_sub_f32_e32 v83, v83, v198
	v_sub_f32_e32 v67, v67, v198
	v_exp_f32_e32 v83, v83
	v_exp_f32_e32 v67, v67
	v_sub_f32_e32 v84, v84, v198
	v_sub_f32_e32 v68, v68, v198
	v_exp_f32_e32 v84, v84
	v_exp_f32_e32 v68, v68
	v_sub_f32_e32 v85, v85, v198
	v_sub_f32_e32 v69, v69, v198
	v_exp_f32_e32 v85, v85
	v_exp_f32_e32 v69, v69
	v_sub_f32_e32 v86, v86, v198
	v_sub_f32_e32 v70, v70, v198
	v_exp_f32_e32 v98, v99
	v_add_f32_e32 v99, v66, v82
	v_exp_f32_e32 v86, v86
	v_exp_f32_e32 v70, v70
	v_sub_f32_e32 v87, v87, v198
	v_sub_f32_e32 v71, v71, v198
	v_add_f32_e32 v99, 0, v99
	v_add_f32_e32 v100, v67, v83
	v_exp_f32_e32 v87, v87
	v_exp_f32_e32 v71, v71
	v_sub_f32_e32 v88, v88, v198
	v_sub_f32_e32 v72, v72, v198
	v_add_f32_e32 v99, v100, v99
	v_add_f32_e32 v100, v68, v84
	v_exp_f32_e32 v88, v88
	v_exp_f32_e32 v72, v72
	v_sub_f32_e32 v89, v89, v198
	v_sub_f32_e32 v73, v73, v198
	v_add_f32_e32 v99, v100, v99
	v_add_f32_e32 v100, v69, v85
	v_exp_f32_e32 v89, v89
	v_exp_f32_e32 v73, v73
	v_sub_f32_e32 v90, v90, v198
	v_sub_f32_e32 v74, v74, v198
	v_add_f32_e32 v99, v100, v99
	v_add_f32_e32 v100, v70, v86
	v_exp_f32_e32 v90, v90
	v_exp_f32_e32 v74, v74
	v_sub_f32_e32 v91, v91, v198
	v_sub_f32_e32 v75, v75, v198
	v_add_f32_e32 v99, v100, v99
	v_add_f32_e32 v100, v71, v87
	v_exp_f32_e32 v91, v91
	v_exp_f32_e32 v75, v75
	v_sub_f32_e32 v92, v92, v198
	v_sub_f32_e32 v76, v76, v198
	v_add_f32_e32 v99, v100, v99
	v_add_f32_e32 v100, v72, v88
	v_exp_f32_e32 v92, v92
	v_exp_f32_e32 v76, v76
	v_sub_f32_e32 v93, v93, v198
	v_sub_f32_e32 v77, v77, v198
	v_add_f32_e32 v99, v100, v99
	v_add_f32_e32 v100, v73, v89
	v_exp_f32_e32 v93, v93
	v_exp_f32_e32 v77, v77
	v_sub_f32_e32 v94, v94, v198
	v_sub_f32_e32 v78, v78, v198
	v_add_f32_e32 v99, v100, v99
	v_add_f32_e32 v100, v74, v90
	v_exp_f32_e32 v94, v94
	v_exp_f32_e32 v78, v78
	v_sub_f32_e32 v95, v95, v198
	v_sub_f32_e32 v79, v79, v198
	v_add_f32_e32 v99, v100, v99
	v_add_f32_e32 v100, v75, v91
	v_exp_f32_e32 v95, v95
	v_exp_f32_e32 v79, v79
	v_sub_f32_e32 v96, v96, v198
	v_sub_f32_e32 v80, v80, v198
	v_add_f32_e32 v99, v100, v99
	v_add_f32_e32 v100, v76, v92
	v_exp_f32_e32 v96, v96
	v_exp_f32_e32 v80, v80
	v_sub_f32_e32 v97, v97, v198
	v_sub_f32_e32 v81, v81, v198
	v_add_f32_e32 v99, v100, v99
	v_add_f32_e32 v100, v77, v93
	v_exp_f32_e32 v97, v97
	v_exp_f32_e32 v81, v81
	v_add_f32_e32 v99, v100, v99
	v_add_f32_e32 v100, v78, v94
	v_add_f32_e32 v99, v100, v99
	v_add_f32_e32 v100, v79, v95
	v_add_f32_e32 v99, v100, v99
	v_add_f32_e32 v100, v80, v96
	v_add_f32_e32 v99, v100, v99
	v_add_f32_e32 v100, v81, v97
	v_add_f32_e32 v237, v100, v99
	v_cndmask_b32_e64 v236, v98, 1.0, vcc
	v_mov_b32_e32 v238, v237
	v_cvt_pk_bf16_f32 v178, v82, v83
	v_cvt_pk_bf16_f32 v179, v84, v85
	v_cvt_pk_bf16_f32 v180, v86, v87
	v_cvt_pk_bf16_f32 v181, v88, v89
	v_cvt_pk_bf16_f32 v182, v90, v91
	v_cvt_pk_bf16_f32 v183, v92, v93
	v_cvt_pk_bf16_f32 v184, v94, v95
	v_cvt_pk_bf16_f32 v185, v96, v97
	v_cvt_pk_bf16_f32 v186, v66, v67
	v_cvt_pk_bf16_f32 v187, v68, v69
	v_cvt_pk_bf16_f32 v188, v70, v71
	v_cvt_pk_bf16_f32 v189, v72, v73
	v_cvt_pk_bf16_f32 v190, v74, v75
	v_cvt_pk_bf16_f32 v191, v76, v77
	v_cvt_pk_bf16_f32 v192, v78, v79
	v_cvt_pk_bf16_f32 v193, v80, v81
	s_nop 1
	v_permlane32_swap_b32_e32 v237, v238
	v_permlane32_swap_b32_e32 v178, v180
	v_permlane32_swap_b32_e32 v179, v181
	v_permlane32_swap_b32_e32 v182, v184
	v_permlane32_swap_b32_e32 v183, v185
	v_permlane32_swap_b32_e32 v186, v188
	v_permlane32_swap_b32_e32 v187, v189
	v_permlane32_swap_b32_e32 v190, v192
	v_permlane32_swap_b32_e32 v191, v193
	v_cmp_gt_f32_e32 vcc, 1.0, v236
	s_cbranch_vccz .LBB0_826
	s_and_saveexec_b64 s[40:41], s[0:1]
	ds_write_b32 v235, v236
	s_or_b64 exec, exec, s[40:41]
	s_waitcnt lgkmcnt(0)
	ds_read_b128 v[66:69], v0 offset:96
	ds_read_b128 v[70:73], v0 offset:64
	ds_read_b128 v[74:77], v0 offset:32
	ds_read_b128 v[78:81], v0
	s_waitcnt lgkmcnt(0)
	v_pk_mul_f32 v[14:15], v[14:15], v[66:67]
	v_pk_mul_f32 v[10:11], v[10:11], v[70:71]
	v_pk_mul_f32 v[6:7], v[6:7], v[74:75]
	v_pk_mul_f32 v[16:17], v[16:17], v[68:69]
	v_pk_mul_f32 v[12:13], v[12:13], v[72:73]
	v_pk_mul_f32 v[8:9], v[8:9], v[76:77]
	v_pk_mul_f32 v[4:5], v[4:5], v[80:81]
	v_pk_mul_f32 v[2:3], v[2:3], v[78:79]
	v_pk_mul_f32 v[62:63], v[62:63], v[66:67]
	v_pk_mul_f32 v[58:59], v[58:59], v[70:71]
	v_pk_mul_f32 v[54:55], v[54:55], v[74:75]
	v_pk_mul_f32 v[64:65], v[64:65], v[68:69]
	v_pk_mul_f32 v[60:61], v[60:61], v[72:73]
	v_pk_mul_f32 v[56:57], v[56:57], v[76:77]
	v_pk_mul_f32 v[52:53], v[52:53], v[80:81]
	v_pk_mul_f32 v[50:51], v[50:51], v[78:79]
	v_pk_mul_f32 v[46:47], v[46:47], v[66:67]
	v_pk_mul_f32 v[42:43], v[42:43], v[70:71]
	v_pk_mul_f32 v[38:39], v[38:39], v[74:75]
	v_pk_mul_f32 v[48:49], v[48:49], v[68:69]
	v_pk_mul_f32 v[44:45], v[44:45], v[72:73]
	v_pk_mul_f32 v[40:41], v[40:41], v[76:77]
	v_pk_mul_f32 v[36:37], v[36:37], v[80:81]
	v_pk_mul_f32 v[34:35], v[34:35], v[78:79]
	v_pk_mul_f32 v[30:31], v[30:31], v[66:67]
	v_pk_mul_f32 v[26:27], v[26:27], v[70:71]
	v_pk_mul_f32 v[22:23], v[22:23], v[74:75]
	v_pk_mul_f32 v[32:33], v[32:33], v[68:69]
	v_pk_mul_f32 v[28:29], v[28:29], v[72:73]
	v_pk_mul_f32 v[24:25], v[24:25], v[76:77]
	v_pk_mul_f32 v[20:21], v[20:21], v[80:81]
	v_pk_mul_f32 v[18:19], v[18:19], v[78:79]
